# weight prep split: only w_ada converted before the first grid sync; w_in/w_o/w_pool converted by the 208 workgroups idle during the adaLN GEMM
# speedup vs baseline: 1.0276x; 1.0276x over previous
.LBB0_5:
	s_or_b64 exec, exec, s[2:3]
	s_mov_b32 s98, 0
	v_readlane_b32 s2, v254, 1
	v_readlane_b32 s3, v254, 2
	s_load_dwordx2 s[18:19], s[2:3], 0x78
	s_load_dwordx4 s[8:11], s[2:3], 0x10
	v_readlane_b32 s12, v254, 0
	s_lshl_b32 s12, s12, 2
	v_mov_b32_e32 v2, v224
	v_writelane_b32 v254, s12, 5
	s_cmpk_gt_i32 s12, 0x1c3f
	s_waitcnt lgkmcnt(0)
	s_mov_b64 s[16:17], s[18:19]
	s_cbranch_scc1 .LBB0_119
	v_lshlrev_b32_e32 v3, 3, v2
	s_load_dwordx2 s[20:21], s[2:3], 0x30
	s_load_dwordx4 s[12:15], s[2:3], 0x50
	s_load_dwordx2 s[22:23], s[2:3], 0x68
	v_ashrrev_i32_e32 v1, 3, v2
	v_and_b32_e32 v26, 56, v3
	s_movk_i32 s2, 0x104
	v_mul_lo_u32 v3, v1, s2
	v_lshlrev_b32_e32 v4, 2, v26
	v_add3_u32 v27, 0, v3, v4
	v_lshlrev_b32_e32 v2, 4, v2
	v_and_b32_e32 v3, 15, v1
	v_and_or_b32 v30, v2, 48, v3
	v_mul_u32_u24_e32 v2, 0x104, v26
	v_lshlrev_b32_e32 v3, 2, v1
	v_add3_u32 v31, 0, v2, v3
	v_mov_b32_e32 v29, 0
	s_mov_b32 s25, 0
	s_lshl_b32 s46, s62, 2
	v_lshlrev_b32_e32 v28, 2, v26
	v_add_u32_e32 v32, 0x400, v31
	v_add_u32_e32 v33, 0x4000, v31
	v_add_u32_e32 v34, 0x4400, v31
	v_add_u32_e32 v35, 0x4200, v31
	v_add_u32_e32 v36, 0x4600, v31
	v_add_u32_e32 v37, 0x8000, v31
	v_add_u32_e32 v38, 0x8400, v31
	v_readlane_b32 s47, v254, 5
	s_mov_b32 s98, 0
	s_mov_b32 s99, s47
	s_movk_i32 s100, 0xc00
	s_addk_i32 s47, 0xc00
	s_branch .LBB0_8
.LBB0_7:
	s_add_i32 s99, s99, s46
	s_cmpk_ge_i32 s99, 0xc00
	s_cselect_b32 s47, 0xc00, 0
	s_cmp_eq_u32 s98, 0
	s_cselect_b32 s47, 0xc00, s47
	s_add_i32 s47, s47, s99
	s_cmp_ge_i32 s99, s100
	s_barrier
	s_cbranch_scc1 .LBB0_119

.LBB0_119:
	s_cmp_lg_u32 s98, 0
	s_cbranch_scc1 .Lpb_done
	v_mov_b32_e32 v1, v224
	s_load_dword s2, s[6:7], 0x10
	s_load_dword s12, s[6:7], 0x0
	v_readlane_b32 s3, v254, 0
	s_mov_b32 s13, 0x40000
	s_waitcnt lgkmcnt(0)
	s_lshr_b32 s2, s2, 16
	s_cmp_lg_u32 s2, 0
	v_lshl_add_u32 v2, s3, 9, v1
	s_cselect_b64 s[2:3], -1, 0
	s_cmp_lg_u64 s[2:3], 0
	s_addc_u32 s2, s12, 0
	s_lshl_b32 s12, s2, 9
	v_cmp_gt_i32_e32 vcc, s13, v2
	v_ashrrev_i32_e32 v3, 31, v2
	s_and_saveexec_b64 s[2:3], vcc
	s_cbranch_execz .LBB0_128
	v_mov_b32_e32 v4, s8
	v_mov_b32_e32 v5, s9
	s_ashr_i32 s13, s12, 31
	v_lshl_add_u64 v[6:7], v[2:3], 1, s[16:17]
	s_mov_b64 s[14:15], 0x3880000
	v_lshl_add_u64 v[4:5], v[2:3], 2, v[4:5]
	s_lshl_b64 s[8:9], s[12:13], 2
	v_lshl_add_u64 v[6:7], v[6:7], 0, s[14:15]
	s_lshl_b64 s[14:15], s[12:13], 1
	s_mov_b64 s[18:19], 0
	s_movk_i32 s13, 0x88
	v_mov_b32_e32 v9, 0
	s_movk_i32 s24, 0x7fff
	s_mov_b32 s25, 0x3ffff
	v_mov_b32_e32 v10, v2
	s_branch .LBB0_122

.Lpb_done:
	v_readlane_b32 s8, v254, 1
	v_readlane_b32 s9, v254, 2
	v_mov_b32_e32 v8, v224
	v_readlane_b32 s2, v254, 0
	s_barrier
	s_cmp_gt_i32 s2, 47
	v_readfirstlane_b32 s30, v8
	s_cbranch_scc1 .Lpb_entry
	v_lshlrev_b32_e32 v0, 4, v8
	v_add_u32_e32 v1, 0x2000, v0
	v_ashrrev_i32_e32 v2, 31, v1
	v_lshrrev_b32_e32 v2, 22, v2
	v_add_u32_e32 v2, v1, v2
	v_ashrrev_i32_e32 v9, 10, v2
	v_mul_i32_i24_e32 v3, 0x400, v9
	v_sub_u32_e32 v1, v1, v3
	v_lshrrev_b32_e32 v3, 4, v1
	s_load_dwordx2 s[10:11], s[8:9], 0x78
	v_bitop3_b32 v1, v3, v1, 32 bitop3:0x6c
	v_ashrrev_i32_e32 v3, 31, v1
	v_lshrrev_b32_e32 v3, 26, v3
	v_add_u32_e32 v3, v1, v3
	v_ashrrev_i32_e32 v10, 6, v3
	v_and_b32_e32 v3, 0xc0, v3
	s_waitcnt lgkmcnt(0)
	s_add_u32 s31, s10, 0x3880000
	v_sub_u32_e32 v1, v1, v3
	v_mov_b32_e32 v3, 1
	s_addc_u32 s34, s11, 0
	v_lshlrev_b32_e32 v2, 5, v9
	v_ashrrev_i16_sdwa v1, v3, sext(v1) dst_sel:DWORD dst_unused:UNUSED_PAD src0_sel:DWORD src1_sel:BYTE_0
	s_add_u32 s35, s10, 0x2000000
	v_and_b32_e32 v2, 32, v2
	v_bfe_i32 v11, v1, 0, 16
	v_readlane_b32 s6, v254, 0
	s_addc_u32 s36, s11, 0
	v_add_u32_e32 v1, v2, v11
	v_lshlrev_b32_e32 v2, 3, v9
	s_ashr_i32 s38, s6, 31
	v_and_b32_e32 v2, 0x1ffff0, v2
	s_lshr_b32 s2, s38, 29
	v_add_lshl_u32 v2, v10, v2, 11
	s_add_i32 s2, s6, s2
	s_ashr_i32 s12, s30, 6
	v_lshl_add_u32 v144, v1, 1, v2
	v_bfe_i32 v2, v8, 27, 1
	s_ashr_i32 s3, s2, 3
	s_and_b32 s2, s2, -8
	s_ashr_i32 s15, s30, 8
	s_lshl_b32 s37, s12, 10
	v_lshrrev_b32_e32 v2, 22, v2
	s_sub_i32 s2, s6, s2
	v_add_u32_e32 v2, v0, v2
	s_cmp_lt_i32 s2, 0
	v_and_b32_e32 v2, 0xfffffc00, v2
	s_cselect_b32 s6, 7, 6
	v_sub_u32_e32 v0, v0, v2
	s_mul_i32 s2, s2, s6
	v_lshrrev_b32_e32 v2, 4, v0
	s_add_i32 s2, s2, s3
	v_bitop3_b32 v2, v2, v0, 32 bitop3:0x6c
	v_ashrrev_i32_e32 v0, 31, v0
	s_mul_hi_i32 s3, s2, 0x2aaaaaab
	v_lshrrev_b32_e32 v0, 26, v0
	s_lshr_b32 s6, s3, 31
	s_ashr_i32 s3, s3, 6
	v_ashrrev_i32_e32 v1, 31, v8
	v_add_u32_e32 v0, v2, v0
	s_add_i32 s3, s3, s6
	v_lshrrev_b32_e32 v1, 26, v1
	v_ashrrev_i32_e32 v13, 6, v0
	s_lshl_b32 s6, s3, 3
	v_add_u32_e32 v1, v8, v1
	v_mul_i32_i24_e32 v0, 64, v13
	s_sub_i32 s7, 1, s6
	s_mulk_i32 s3, 0x180
	v_ashrrev_i32_e32 v12, 6, v1
	v_sub_u32_e32 v0, v2, v0
	s_min_u32 s7, s7, 8
	s_sub_i32 s13, s2, s3
	v_lshlrev_b32_e32 v1, 5, v12
	v_ashrrev_i16_sdwa v0, v3, sext(v0) dst_sel:DWORD dst_unused:UNUSED_PAD src0_sel:DWORD src1_sel:BYTE_0
	s_sext_i32_i16 s2, s13
	v_cvt_f32_ubyte0_e32 v3, s7
	v_and_b32_e32 v1, 32, v1
	v_bfe_i32 v14, v0, 0, 16
	v_cvt_f32_i32_e32 v2, s2
	v_rcp_iflag_f32_e32 v4, v3
	v_add_u32_e32 v0, v1, v14
	v_lshlrev_b32_e32 v1, 3, v12
	v_and_b32_e32 v1, 0x1ffff0, v1
	v_add_lshl_u32 v1, v13, v1, 11
	v_lshl_add_u32 v146, v0, 1, v1
	v_mul_f32_e32 v0, v2, v4
	v_trunc_f32_e32 v0, v0
	v_fma_f32 v1, -v0, v3, v2
	v_cvt_i32_f32_e32 v0, v0
	s_ashr_i32 s2, s2, 30
	s_or_b32 s14, s2, 1
	v_cmp_ge_f32_e64 s[2:3], |v1|, v3
	s_and_b64 s[2:3], s[2:3], exec
	s_cselect_b32 s2, s14, 0
	v_readfirstlane_b32 s3, v0
	s_add_i32 s14, s3, s2
	s_mul_i32 s2, s14, s7
	s_sub_i32 s2, s13, s2
	s_sext_i32_i16 s2, s2
	s_add_i32 s26, s6, s2
	s_ashr_i32 s27, s26, 31
	s_bfe_i64 s[2:3], s[14:15], 0x100000
	s_lshl_b64 s[6:7], s[26:27], 19
	s_lshl_b64 s[2:3], s[2:3], 19
	s_add_u32 s2, s35, s2
	s_addc_u32 s3, s36, s3
	s_add_i32 s27, s37, 0
	s_add_i32 m0, s27, 0x10000
	s_load_dwordx2 s[8:9], s[8:9], 0x38
	global_load_lds_dwordx4 v146, s[2:3]
	s_add_i32 m0, s27, 0x12000
	s_add_u32 s6, s31, s6
	global_load_lds_dwordx4 v144, s[2:3]
	s_addc_u32 s7, s34, s7
	s_mov_b32 m0, s27
	s_add_i32 s39, s27, 0x2000
	global_load_lds_dwordx4 v146, s[6:7]
	s_mov_b32 m0, s39
	s_add_u32 s16, s2, 0x40000
	global_load_lds_dwordx4 v144, s[6:7]
	s_addc_u32 s17, s3, 0
	s_add_i32 m0, s27, 0x14000
	v_mov_b32_e32 v147, 0
	global_load_lds_dwordx4 v146, s[16:17]
	s_add_i32 m0, s27, 0x16000
	v_mov_b32_e32 v145, v147
	global_load_lds_dwordx4 v144, s[16:17]
	s_add_u32 s16, s6, 0x40000
	s_addc_u32 s17, s7, 0
	s_add_i32 s40, s27, 0x4000
	s_mov_b32 m0, s40
	s_add_i32 s41, s27, 0x6000
	global_load_lds_dwordx4 v146, s[16:17]
	s_mov_b32 m0, s41
	s_mov_b32 s42, 0
	global_load_lds_dwordx4 v144, s[16:17]
	v_lshl_add_u64 v[6:7], s[2:3], 0, v[146:147]
	v_lshl_add_u64 v[4:5], s[2:3], 0, v[144:145]
	v_lshl_add_u64 v[2:3], s[6:7], 0, v[146:147]
	s_cmp_lg_u32 s15, 1
	v_lshl_add_u64 v[0:1], s[6:7], 0, v[144:145]
	s_cbranch_scc1 .LBB0_152
	s_barrier

.LBB0_168:
	s_barrier
	s_branch .LBB0_169
.Lpb_entry:
	s_cmp_lg_u32 s98, 0
	s_cbranch_scc1 .LBB0_169
	s_mov_b32 s98, 1
	v_readlane_b32 s2, v254, 1
	v_readlane_b32 s3, v254, 2
	s_nop 4
	s_load_dwordx2 s[18:19], s[2:3], 0x78
	s_load_dwordx2 s[20:21], s[2:3], 0x30
	s_load_dwordx4 s[12:15], s[2:3], 0x50
	s_load_dwordx2 s[22:23], s[2:3], 0x68
	v_mov_b32_e32 v2, v224
	v_lshlrev_b32_e32 v3, 3, v2
	v_ashrrev_i32_e32 v1, 3, v2
	v_and_b32_e32 v26, 56, v3
	v_readlane_b32 s99, v254, 0
	s_movk_i32 s2, 0x104
	v_mul_lo_u32 v3, v1, s2
	v_lshlrev_b32_e32 v4, 2, v26
	v_add3_u32 v27, 0, v3, v4
	v_lshlrev_b32_e32 v2, 4, v2
	v_and_b32_e32 v3, 15, v1
	v_and_or_b32 v30, v2, 48, v3
	v_mul_u32_u24_e32 v2, 0x104, v26
	v_lshlrev_b32_e32 v3, 2, v1
	v_add3_u32 v31, 0, v2, v3
	v_mov_b32_e32 v29, 0
	s_mov_b32 s25, 0
	s_sub_i32 s46, s62, 48
	s_lshl_b32 s46, s46, 2
	v_lshlrev_b32_e32 v28, 2, v26
	v_add_u32_e32 v32, 0x400, v31
	v_add_u32_e32 v33, 0x4000, v31
	v_add_u32_e32 v34, 0x4400, v31
	v_add_u32_e32 v35, 0x4200, v31
	v_add_u32_e32 v36, 0x4600, v31
	v_add_u32_e32 v37, 0x8000, v31
	v_add_u32_e32 v38, 0x8400, v31
	s_sub_i32 s99, s99, 48
	s_lshl_b32 s99, s99, 2
	s_movk_i32 s100, 0x1040
	s_mov_b32 s47, s99
	s_waitcnt lgkmcnt(0)
	s_mov_b64 s[16:17], s[18:19]
	s_branch .LBB0_8
